# gate/up GEMM: 4 of the 8 epilogue stores per tile deferred (spare VGPRs) into the next tile's K-loop
# baseline (speedup 1.0000x reference)
.LBB0_851:
	s_lshl_b32 s12, s12, 5
	s_and_b32 s18, s12, 0x60
	s_mov_b64 s[12:13], 0x80
	s_add_i32 m0, s25, 0x18000
	v_lshl_add_u64 v[6:7], v[6:7], 0, s[12:13]
	s_lshl_b32 s15, s14, 13
	s_lshl_b32 s19, s18, 7
	s_waitcnt vmcnt(2)
	s_barrier
	global_load_lds_dwordx4 v[6:7], off
	v_lshl_add_u64 v[4:5], v[4:5], 0, s[12:13]
	s_add_i32 m0, s25, 0x1a000
	s_add_i32 s38, s25, 0x8000
	s_add_i32 s39, s25, 0xa000
	global_load_lds_dwordx4 v[4:5], off
	v_lshl_add_u64 v[0:1], v[0:1], 0, s[12:13]
	s_mov_b32 m0, s38
	s_add_u32 s16, s28, 0x40080
	global_load_lds_dwordx4 v[0:1], off
	v_lshl_add_u64 v[0:1], v[2:3], 0, s[12:13]
	s_mov_b32 m0, s39
	s_addc_u32 s17, s29, 0
	global_load_lds_dwordx4 v[0:1], off
	s_add_i32 m0, s25, 0x1c000
	v_lshl_add_u64 v[0:1], s[16:17], 0, v[134:135]
	global_load_lds_dwordx4 v[0:1], off
	v_lshl_add_u64 v[0:1], s[16:17], 0, v[130:131]
	s_add_i32 m0, s25, 0x1e000
	s_cmpk_lt_u32 s5, 0x100
	global_load_lds_dwordx4 v[0:1], off
	v_lshrrev_b32_e32 v1, 1, v10
	v_and_b32_e32 v1, 24, v1
	v_and_b32_e32 v0, 15, v10
	v_lshlrev_b32_e32 v2, 1, v1
	v_lshl_or_b32 v129, s14, 6, v0
	v_lshl_or_b32 v0, v0, 6, v2
	v_lshlrev_b32_e32 v2, 2, v10
	v_and_b32_e32 v2, 32, v2
	v_bitop3_b32 v3, v0, s15, v2 bitop3:0xde
	v_bitop3_b32 v148, v0, s19, v2 bitop3:0xde
	v_lshlrev_b32_e32 v0, 14, v13
	v_and_b32_e32 v0, 0xffff8000, v0
	v_or_b32_e32 v149, s18, v1
	v_lshl_add_u32 v0, v12, 11, v0
	v_and_b32_e32 v1, 1, v13
	v_lshl_or_b32 v0, v1, 6, v0
	v_lshl_add_u32 v138, v14, 1, v0
	v_lshlrev_b32_e32 v0, 14, v8
	v_and_b32_e32 v0, 0xffff8000, v0
	s_waitcnt vmcnt(6)
	v_lshl_add_u32 v0, v9, 11, v0
	v_and_b32_e32 v1, 1, v8
	s_cselect_b64 s[14:15], -1, 0
	v_lshl_or_b32 v0, v1, 6, v0
	s_add_i32 s42, 0, 0x10000
	s_add_i32 s43, 0, 0x14000
	s_sext_i32_i16 s45, s4
	s_ashr_i32 s40, s84, 31
	s_mov_b32 s41, s84
	v_mov_b32_e32 v139, v135
	v_lshl_add_u32 v140, v11, 1, v0
	v_mov_b32_e32 v141, v135
	v_mov_b64_e32 v[142:143], 0x1600
	v_mov_b64_e32 v[146:147], 0x15ff
	v_add_u32_e32 v150, s42, v148
	v_add_u32_e32 v151, s43, v148
	v_add_u32_e32 v152, 0, v3
	s_movk_i32 s44, 0x1600
	s_mov_b32 s98, 0
	s_barrier
	s_branch .LBB0_854

.LBB0_857:
	ds_read_b128 v[154:157], v150
	ds_read_b128 v[158:161], v150 offset:1024
	ds_read_b128 v[164:167], v150 offset:2048
	ds_read_b128 v[168:171], v150 offset:3072
	ds_read_b128 v[172:175], v151
	ds_read_b128 v[176:179], v151 offset:1024
	ds_read_b128 v[180:183], v151 offset:2048
	ds_read_b128 v[184:187], v151 offset:3072
	s_add_u32 s28, s26, 0xfffc0080
	s_addc_u32 s29, s27, -1
	s_cmp_eq_u32 s50, 12
	s_cselect_b32 s31, s19, s29
	s_cselect_b32 s30, s46, s28
	s_cselect_b32 s29, s17, s49
	s_cselect_b32 s28, s47, s48
	s_cmp_eq_u32 s98, 0
	s_cbranch_scc1 .Lp7d_done
	s_cmp_eq_u32 s50, 0
	s_cbranch_scc0 .Lp7d_n0
	global_store_dwordx4 v[230:231], v[238:241], off
.Lp7d_n0:
	s_cmp_eq_u32 s50, 2
	s_cbranch_scc0 .Lp7d_n1
	global_store_dwordx4 v[232:233], v[242:245], off
.Lp7d_n1:
	s_cmp_eq_u32 s50, 4
	s_cbranch_scc0 .Lp7d_n2
	global_store_dwordx4 v[234:235], v[246:249], off
.Lp7d_n2:
	s_cmp_eq_u32 s50, 6
	s_cbranch_scc0 .Lp7d_done
	global_store_dwordx4 v[236:237], v[250:253], off
	s_mov_b32 s98, 0
.Lp7d_done:
	v_lshl_add_u64 v[220:221], s[26:27], 0, v[138:139]
	s_add_i32 m0, s25, 0xc000
	ds_read_b128 v[188:191], v152
	ds_read_b128 v[192:195], v152 offset:1024
	ds_read_b128 v[196:199], v152 offset:2048
	ds_read_b128 v[200:203], v152 offset:3072
	ds_read_b128 v[204:207], v152 offset:4096
	ds_read_b128 v[208:211], v152 offset:5120
	ds_read_b128 v[212:215], v152 offset:6144
	ds_read_b128 v[216:219], v152 offset:7168
	global_load_lds_dwordx4 v[220:221], off
	v_lshl_add_u64 v[220:221], s[26:27], 0, v[140:141]
	s_add_i32 m0, s25, 0xe000
	s_nop 0
	global_load_lds_dwordx4 v[220:221], off
	s_waitcnt vmcnt(8)
	s_waitcnt lgkmcnt(0)
	s_barrier
	s_setprio 1
	s_waitcnt lgkmcnt(0)
	v_mfma_f32_16x16x32_bf16 v[124:127], v[154:157], v[188:191], v[124:127]
	v_mfma_f32_16x16x32_bf16 v[120:123], v[164:167], v[188:191], v[120:123]
	v_mfma_f32_16x16x32_bf16 v[108:111], v[154:157], v[196:199], v[108:111]
	v_mfma_f32_16x16x32_bf16 v[104:107], v[164:167], v[196:199], v[104:107]
	v_mfma_f32_16x16x32_bf16 v[92:95], v[154:157], v[204:207], v[92:95]
	v_mfma_f32_16x16x32_bf16 v[88:91], v[164:167], v[204:207], v[88:91]
	v_mfma_f32_16x16x32_bf16 v[76:79], v[154:157], v[212:215], v[76:79]
	v_mfma_f32_16x16x32_bf16 v[72:75], v[164:167], v[212:215], v[72:75]
	v_mfma_f32_16x16x32_bf16 v[124:127], v[158:161], v[192:195], v[124:127]
	v_mfma_f32_16x16x32_bf16 v[120:123], v[168:171], v[192:195], v[120:123]
	v_mfma_f32_16x16x32_bf16 v[108:111], v[158:161], v[200:203], v[108:111]
	v_mfma_f32_16x16x32_bf16 v[104:107], v[168:171], v[200:203], v[104:107]
	v_mfma_f32_16x16x32_bf16 v[92:95], v[158:161], v[208:211], v[92:95]
	v_mfma_f32_16x16x32_bf16 v[88:91], v[168:171], v[208:211], v[88:91]
	v_mfma_f32_16x16x32_bf16 v[76:79], v[158:161], v[216:219], v[76:79]
	v_mfma_f32_16x16x32_bf16 v[72:75], v[168:171], v[216:219], v[72:75]
	s_setprio 0
	s_setprio 1
	v_mfma_f32_16x16x32_bf16 v[116:119], v[172:175], v[188:191], v[116:119]
	v_mfma_f32_16x16x32_bf16 v[112:115], v[180:183], v[188:191], v[112:115]
	v_mfma_f32_16x16x32_bf16 v[100:103], v[172:175], v[196:199], v[100:103]
	v_mfma_f32_16x16x32_bf16 v[96:99], v[180:183], v[196:199], v[96:99]
	v_mfma_f32_16x16x32_bf16 v[84:87], v[172:175], v[204:207], v[84:87]
	v_mfma_f32_16x16x32_bf16 v[80:83], v[180:183], v[204:207], v[80:83]
	v_mfma_f32_16x16x32_bf16 v[68:71], v[172:175], v[212:215], v[68:71]
	v_mfma_f32_16x16x32_bf16 v[64:67], v[180:183], v[212:215], v[64:67]
	v_mfma_f32_16x16x32_bf16 v[116:119], v[176:179], v[192:195], v[116:119]
	v_mfma_f32_16x16x32_bf16 v[112:115], v[184:187], v[192:195], v[112:115]
	v_mfma_f32_16x16x32_bf16 v[100:103], v[176:179], v[200:203], v[100:103]
	v_mfma_f32_16x16x32_bf16 v[96:99], v[184:187], v[200:203], v[96:99]
	v_mfma_f32_16x16x32_bf16 v[84:87], v[176:179], v[208:211], v[84:87]
	v_mfma_f32_16x16x32_bf16 v[80:83], v[184:187], v[208:211], v[80:83]
	v_mfma_f32_16x16x32_bf16 v[68:71], v[176:179], v[216:219], v[68:71]
	v_mfma_f32_16x16x32_bf16 v[64:67], v[184:187], v[216:219], v[64:67]
	s_setprio 0
	s_barrier
	s_add_i32 s51, s42, s2
	v_lshl_add_u64 v[220:221], s[28:29], 0, v[134:135]
	s_mov_b32 m0, s51
	ds_read_b128 v[188:191], v152 offset:16384
	ds_read_b128 v[192:195], v152 offset:17408
	ds_read_b128 v[196:199], v152 offset:18432
	ds_read_b128 v[200:203], v152 offset:19456
	ds_read_b128 v[204:207], v152 offset:20480
	ds_read_b128 v[208:211], v152 offset:21504
	ds_read_b128 v[212:215], v152 offset:22528
	ds_read_b128 v[216:219], v152 offset:23552
	global_load_lds_dwordx4 v[220:221], off
	s_add_i32 m0, s51, 0x2000
	s_add_u32 s52, s28, 0x40000
	v_lshl_add_u64 v[222:223], s[28:29], 0, v[130:131]
	s_addc_u32 s53, s29, 0
	s_add_i32 s51, s43, s2
	global_load_lds_dwordx4 v[222:223], off
	v_lshl_add_u64 v[224:225], s[52:53], 0, v[134:135]
	s_mov_b32 m0, s51
	v_lshl_add_u64 v[226:227], s[30:31], 0, v[132:133]
	global_load_lds_dwordx4 v[224:225], off
	v_lshl_add_u64 v[224:225], s[52:53], 0, v[130:131]
	s_add_i32 m0, s51, 0x2000
	s_nop 0
	global_load_lds_dwordx4 v[224:225], off
	v_lshl_add_u64 v[224:225], s[30:31], 0, v[136:137]
	s_mov_b32 m0, s25
	s_nop 0
	global_load_lds_dwordx4 v[224:225], off
	s_mov_b32 m0, s34
	s_nop 0
	global_load_lds_dwordx4 v[226:227], off
	s_waitcnt vmcnt(8)
	s_waitcnt lgkmcnt(0)
	s_barrier
	s_setprio 1
	s_waitcnt lgkmcnt(0)
	v_mfma_f32_16x16x32_bf16 v[60:63], v[154:157], v[188:191], v[60:63]
	v_mfma_f32_16x16x32_bf16 v[56:59], v[164:167], v[188:191], v[56:59]
	v_mfma_f32_16x16x32_bf16 v[44:47], v[154:157], v[196:199], v[44:47]
	v_mfma_f32_16x16x32_bf16 v[40:43], v[164:167], v[196:199], v[40:43]
	v_mfma_f32_16x16x32_bf16 v[28:31], v[154:157], v[204:207], v[28:31]
	v_mfma_f32_16x16x32_bf16 v[24:27], v[164:167], v[204:207], v[24:27]
	v_mfma_f32_16x16x32_bf16 v[12:15], v[154:157], v[212:215], v[12:15]
	v_mfma_f32_16x16x32_bf16 v[8:11], v[164:167], v[212:215], v[8:11]
	v_mfma_f32_16x16x32_bf16 v[60:63], v[158:161], v[192:195], v[60:63]
	v_mfma_f32_16x16x32_bf16 v[56:59], v[168:171], v[192:195], v[56:59]
	v_mfma_f32_16x16x32_bf16 v[44:47], v[158:161], v[200:203], v[44:47]
	v_mfma_f32_16x16x32_bf16 v[40:43], v[168:171], v[200:203], v[40:43]
	v_mfma_f32_16x16x32_bf16 v[28:31], v[158:161], v[208:211], v[28:31]
	v_mfma_f32_16x16x32_bf16 v[24:27], v[168:171], v[208:211], v[24:27]
	v_mfma_f32_16x16x32_bf16 v[12:15], v[158:161], v[216:219], v[12:15]
	v_mfma_f32_16x16x32_bf16 v[8:11], v[168:171], v[216:219], v[8:11]
	s_setprio 0
	s_setprio 1
	v_mfma_f32_16x16x32_bf16 v[52:55], v[172:175], v[188:191], v[52:55]
	v_mfma_f32_16x16x32_bf16 v[48:51], v[180:183], v[188:191], v[48:51]
	v_mfma_f32_16x16x32_bf16 v[36:39], v[172:175], v[196:199], v[36:39]
	v_mfma_f32_16x16x32_bf16 v[32:35], v[180:183], v[196:199], v[32:35]
	v_mfma_f32_16x16x32_bf16 v[20:23], v[172:175], v[204:207], v[20:23]
	v_mfma_f32_16x16x32_bf16 v[16:19], v[180:183], v[204:207], v[16:19]
	v_mfma_f32_16x16x32_bf16 v[4:7], v[172:175], v[212:215], v[4:7]
	v_mfma_f32_16x16x32_bf16 v[0:3], v[180:183], v[212:215], v[0:3]
	v_mfma_f32_16x16x32_bf16 v[52:55], v[176:179], v[192:195], v[52:55]
	v_mfma_f32_16x16x32_bf16 v[48:51], v[184:187], v[192:195], v[48:51]
	v_mfma_f32_16x16x32_bf16 v[36:39], v[176:179], v[200:203], v[36:39]
	v_mfma_f32_16x16x32_bf16 v[32:35], v[184:187], v[200:203], v[32:35]
	v_mfma_f32_16x16x32_bf16 v[20:23], v[176:179], v[208:211], v[20:23]
	v_mfma_f32_16x16x32_bf16 v[16:19], v[184:187], v[208:211], v[16:19]
	v_mfma_f32_16x16x32_bf16 v[4:7], v[176:179], v[216:219], v[4:7]
	v_mfma_f32_16x16x32_bf16 v[0:3], v[184:187], v[216:219], v[0:3]
	s_setprio 0
	s_barrier
	s_add_i32 s51, 0, 0x18000
	v_add_u32_e32 v153, s51, v148
	s_add_i32 s52, 0, 0x1c000
	ds_read_b128 v[154:157], v153
	ds_read_b128 v[158:161], v153 offset:1024
	ds_read_b128 v[164:167], v153 offset:2048
	ds_read_b128 v[168:171], v153 offset:3072
	v_add_u32_e32 v153, s52, v148
	ds_read_b128 v[172:175], v153
	ds_read_b128 v[176:179], v153 offset:1024
	ds_read_b128 v[180:183], v153 offset:2048
	ds_read_b128 v[184:187], v153 offset:3072
	s_add_u32 s30, s30, 0x40000
	s_addc_u32 s31, s31, 0
	s_mov_b32 m0, s35
	v_lshl_add_u64 v[228:229], s[30:31], 0, v[136:137]
	ds_read_b128 v[188:191], v152 offset:32768
	ds_read_b128 v[192:195], v152 offset:33792
	ds_read_b128 v[196:199], v152 offset:34816
	ds_read_b128 v[200:203], v152 offset:35840
	ds_read_b128 v[204:207], v152 offset:36864
	ds_read_b128 v[208:211], v152 offset:37888
	ds_read_b128 v[212:215], v152 offset:38912
	ds_read_b128 v[216:219], v152 offset:39936
	global_load_lds_dwordx4 v[228:229], off
	v_lshl_add_u64 v[228:229], s[30:31], 0, v[132:133]
	s_mov_b32 m0, s36
	s_nop 0
	global_load_lds_dwordx4 v[228:229], off
	s_waitcnt vmcnt(8)
	s_waitcnt lgkmcnt(0)
	s_barrier
	s_setprio 1
	s_waitcnt lgkmcnt(0)
	v_mfma_f32_16x16x32_bf16 v[124:127], v[154:157], v[188:191], v[124:127]
	v_mfma_f32_16x16x32_bf16 v[120:123], v[164:167], v[188:191], v[120:123]
	v_mfma_f32_16x16x32_bf16 v[108:111], v[154:157], v[196:199], v[108:111]
	v_mfma_f32_16x16x32_bf16 v[104:107], v[164:167], v[196:199], v[104:107]
	v_mfma_f32_16x16x32_bf16 v[92:95], v[154:157], v[204:207], v[92:95]
	v_mfma_f32_16x16x32_bf16 v[88:91], v[164:167], v[204:207], v[88:91]
	v_mfma_f32_16x16x32_bf16 v[76:79], v[154:157], v[212:215], v[76:79]
	v_mfma_f32_16x16x32_bf16 v[72:75], v[164:167], v[212:215], v[72:75]
	v_mfma_f32_16x16x32_bf16 v[124:127], v[158:161], v[192:195], v[124:127]
	v_mfma_f32_16x16x32_bf16 v[120:123], v[168:171], v[192:195], v[120:123]
	v_mfma_f32_16x16x32_bf16 v[108:111], v[158:161], v[200:203], v[108:111]
	v_mfma_f32_16x16x32_bf16 v[104:107], v[168:171], v[200:203], v[104:107]
	v_mfma_f32_16x16x32_bf16 v[92:95], v[158:161], v[208:211], v[92:95]
	v_mfma_f32_16x16x32_bf16 v[88:91], v[168:171], v[208:211], v[88:91]
	v_mfma_f32_16x16x32_bf16 v[76:79], v[158:161], v[216:219], v[76:79]
	v_mfma_f32_16x16x32_bf16 v[72:75], v[168:171], v[216:219], v[72:75]
	s_setprio 0
	s_setprio 1
	v_mfma_f32_16x16x32_bf16 v[116:119], v[172:175], v[188:191], v[116:119]
	v_mfma_f32_16x16x32_bf16 v[112:115], v[180:183], v[188:191], v[112:115]
	v_mfma_f32_16x16x32_bf16 v[100:103], v[172:175], v[196:199], v[100:103]
	v_mfma_f32_16x16x32_bf16 v[96:99], v[180:183], v[196:199], v[96:99]
	v_mfma_f32_16x16x32_bf16 v[84:87], v[172:175], v[204:207], v[84:87]
	v_mfma_f32_16x16x32_bf16 v[80:83], v[180:183], v[204:207], v[80:83]
	v_mfma_f32_16x16x32_bf16 v[68:71], v[172:175], v[212:215], v[68:71]
	v_mfma_f32_16x16x32_bf16 v[64:67], v[180:183], v[212:215], v[64:67]
	v_mfma_f32_16x16x32_bf16 v[116:119], v[176:179], v[192:195], v[116:119]
	v_mfma_f32_16x16x32_bf16 v[112:115], v[184:187], v[192:195], v[112:115]
	v_mfma_f32_16x16x32_bf16 v[100:103], v[176:179], v[200:203], v[100:103]
	v_mfma_f32_16x16x32_bf16 v[96:99], v[184:187], v[200:203], v[96:99]
	v_mfma_f32_16x16x32_bf16 v[84:87], v[176:179], v[208:211], v[84:87]
	v_mfma_f32_16x16x32_bf16 v[80:83], v[184:187], v[208:211], v[80:83]
	v_mfma_f32_16x16x32_bf16 v[68:71], v[176:179], v[216:219], v[68:71]
	v_mfma_f32_16x16x32_bf16 v[64:67], v[184:187], v[216:219], v[64:67]
	s_setprio 0
	s_barrier
	s_add_i32 s30, s51, s2
	v_lshl_add_u64 v[220:221], v[220:221], 0, s[12:13]
	s_mov_b32 m0, s30
	ds_read_b128 v[188:191], v152 offset:49152
	ds_read_b128 v[192:195], v152 offset:50176
	ds_read_b128 v[196:199], v152 offset:51200
	ds_read_b128 v[200:203], v152 offset:52224
	ds_read_b128 v[204:207], v152 offset:53248
	ds_read_b128 v[208:211], v152 offset:54272
	ds_read_b128 v[212:215], v152 offset:55296
	ds_read_b128 v[216:219], v152 offset:56320
	global_load_lds_dwordx4 v[220:221], off
	s_add_i32 m0, s30, 0x2000
	s_add_u32 s28, s28, 0x40080
	v_lshl_add_u64 v[220:221], v[222:223], 0, s[12:13]
	s_addc_u32 s29, s29, 0
	s_add_i32 s30, s52, s2
	global_load_lds_dwordx4 v[220:221], off
	v_lshl_add_u64 v[220:221], s[28:29], 0, v[134:135]
	s_mov_b32 m0, s30
	s_nop 0
	global_load_lds_dwordx4 v[220:221], off
	v_lshl_add_u64 v[220:221], s[28:29], 0, v[130:131]
	s_add_i32 m0, s30, 0x2000
	s_nop 0
	global_load_lds_dwordx4 v[220:221], off
	v_lshl_add_u64 v[220:221], v[224:225], 0, s[12:13]
	s_mov_b32 m0, s38
	s_nop 0
	global_load_lds_dwordx4 v[220:221], off
	v_lshl_add_u64 v[220:221], v[226:227], 0, s[12:13]
	s_mov_b32 m0, s39
	s_nop 0
	global_load_lds_dwordx4 v[220:221], off
	s_waitcnt vmcnt(8)
	s_waitcnt lgkmcnt(0)
	s_barrier
	s_setprio 1
	s_waitcnt lgkmcnt(0)
	v_mfma_f32_16x16x32_bf16 v[60:63], v[154:157], v[188:191], v[60:63]
	v_mfma_f32_16x16x32_bf16 v[56:59], v[164:167], v[188:191], v[56:59]
	v_mfma_f32_16x16x32_bf16 v[44:47], v[154:157], v[196:199], v[44:47]
	v_mfma_f32_16x16x32_bf16 v[40:43], v[164:167], v[196:199], v[40:43]
	v_mfma_f32_16x16x32_bf16 v[28:31], v[154:157], v[204:207], v[28:31]
	v_mfma_f32_16x16x32_bf16 v[24:27], v[164:167], v[204:207], v[24:27]
	v_mfma_f32_16x16x32_bf16 v[12:15], v[154:157], v[212:215], v[12:15]
	v_mfma_f32_16x16x32_bf16 v[8:11], v[164:167], v[212:215], v[8:11]
	v_mfma_f32_16x16x32_bf16 v[60:63], v[158:161], v[192:195], v[60:63]
	v_mfma_f32_16x16x32_bf16 v[56:59], v[168:171], v[192:195], v[56:59]
	v_mfma_f32_16x16x32_bf16 v[44:47], v[158:161], v[200:203], v[44:47]
	v_mfma_f32_16x16x32_bf16 v[40:43], v[168:171], v[200:203], v[40:43]
	v_mfma_f32_16x16x32_bf16 v[28:31], v[158:161], v[208:211], v[28:31]
	v_mfma_f32_16x16x32_bf16 v[24:27], v[168:171], v[208:211], v[24:27]
	v_mfma_f32_16x16x32_bf16 v[12:15], v[158:161], v[216:219], v[12:15]
	v_mfma_f32_16x16x32_bf16 v[8:11], v[168:171], v[216:219], v[8:11]
	s_setprio 0
	s_setprio 1
	v_mfma_f32_16x16x32_bf16 v[52:55], v[172:175], v[188:191], v[52:55]
	v_mfma_f32_16x16x32_bf16 v[48:51], v[180:183], v[188:191], v[48:51]
	v_mfma_f32_16x16x32_bf16 v[36:39], v[172:175], v[196:199], v[36:39]
	v_mfma_f32_16x16x32_bf16 v[32:35], v[180:183], v[196:199], v[32:35]
	v_mfma_f32_16x16x32_bf16 v[20:23], v[172:175], v[204:207], v[20:23]
	v_mfma_f32_16x16x32_bf16 v[16:19], v[180:183], v[204:207], v[16:19]
	v_mfma_f32_16x16x32_bf16 v[4:7], v[172:175], v[212:215], v[4:7]
	v_mfma_f32_16x16x32_bf16 v[0:3], v[180:183], v[212:215], v[0:3]
	v_mfma_f32_16x16x32_bf16 v[52:55], v[176:179], v[192:195], v[52:55]
	v_mfma_f32_16x16x32_bf16 v[48:51], v[184:187], v[192:195], v[48:51]
	v_mfma_f32_16x16x32_bf16 v[36:39], v[176:179], v[200:203], v[36:39]
	v_mfma_f32_16x16x32_bf16 v[32:35], v[184:187], v[200:203], v[32:35]
	v_mfma_f32_16x16x32_bf16 v[20:23], v[176:179], v[208:211], v[20:23]
	v_mfma_f32_16x16x32_bf16 v[16:19], v[184:187], v[208:211], v[16:19]
	v_mfma_f32_16x16x32_bf16 v[4:7], v[176:179], v[216:219], v[4:7]
	v_mfma_f32_16x16x32_bf16 v[0:3], v[184:187], v[216:219], v[0:3]
	s_setprio 0
	s_barrier
	s_add_i32 s50, s50, 2
	s_add_u32 s26, s26, 0x100
	s_addc_u32 s27, s27, 0
	s_add_u32 s48, s48, 0x100
	s_addc_u32 s49, s49, 0
	s_cmp_gt_u32 s50, 13
	s_cbranch_scc0 .LBB0_857
	s_and_b64 vcc, exec, s[14:15]
	s_cbranch_vccz .LBB0_860
	s_barrier
.LBB0_860:
	v_mul_f32_e32 v156, 0xbfb8aa3b, v124
	v_mul_f32_e32 v157, 0xbfb8aa3b, v120
	v_mul_f32_e32 v158, 0xbfb8aa3b, v125
	v_exp_f32_e32 v156, v156
	v_exp_f32_e32 v157, v157
	v_exp_f32_e32 v158, v158
	v_lshl_or_b32 v154, s45, 7, v149
	v_add_f32_e32 v156, 1.0, v156
	v_add_f32_e32 v159, 1.0, v157
	v_add_f32_e32 v157, 1.0, v158
	v_rcp_f32_e32 v156, v156
	v_rcp_f32_e32 v157, v157
	v_mul_f32_e32 v158, 0xbfb8aa3b, v121
	v_exp_f32_e32 v160, v158
	v_rcp_f32_e32 v158, v159
	v_pk_mul_f32 v[124:125], v[124:125], v[156:157]
	v_mul_f32_e32 v156, 0xbfb8aa3b, v127
	v_pk_mul_f32 v[116:117], v[124:125], v[116:117]
	v_add_f32_e32 v124, 1.0, v160
	v_rcp_f32_e32 v159, v124
	v_mul_f32_e32 v125, 0xbfb8aa3b, v122
	v_mul_f32_e32 v124, 0xbfb8aa3b, v126
	v_exp_f32_e32 v125, v125
	v_exp_f32_e32 v124, v124
	v_exp_f32_e32 v157, v156
	v_mul_f32_e32 v156, 0xbfb8aa3b, v123
	v_pk_mul_f32 v[120:121], v[120:121], v[158:159]
	v_exp_f32_e32 v158, v156
	v_add_f32_e32 v125, 1.0, v125
	v_add_f32_e32 v124, 1.0, v124
	v_rcp_f32_e32 v156, v125
	v_add_f32_e32 v125, 1.0, v157
	v_rcp_f32_e32 v124, v124
	v_rcp_f32_e32 v125, v125
	v_add_f32_e32 v157, 1.0, v158
	v_rcp_f32_e32 v157, v157
	v_pk_mul_f32 v[112:113], v[120:121], v[112:113]
	v_pk_mul_f32 v[120:121], v[126:127], v[124:125]
	v_lshl_add_u32 v153, s24, 8, v129
	v_pk_mul_f32 v[118:119], v[120:121], v[118:119]
	v_pk_mul_f32 v[120:121], v[122:123], v[156:157]
	v_ashrrev_i32_e32 v155, 31, v154
	v_pk_mul_f32 v[114:115], v[120:121], v[114:115]
	v_cvt_pk_bf16_f32 v116, v116, v117
	v_cvt_pk_bf16_f32 v117, v118, v119
	v_cvt_pk_bf16_f32 v118, v112, v113
	v_mov_b64_e32 v[112:113], s[10:11]
	v_cvt_pk_bf16_f32 v119, v114, v115
	v_mad_i64_i32 v[120:121], s[26:27], v153, s44, v[112:113]
	v_lshlrev_b64 v[114:115], 1, v[154:155]
	v_lshl_add_u64 v[120:121], v[120:121], 0, v[114:115]
	global_store_dwordx4 v[120:121], v[116:119], off
	s_andn2_b64 vcc, exec, s[4:5]
	s_mov_b64 s[4:5], -1
	v_mul_f32_e32 v116, 0xbfb8aa3b, v108
	v_mul_f32_e32 v117, 0xbfb8aa3b, v104
	v_mul_f32_e32 v118, 0xbfb8aa3b, v109
	v_exp_f32_e32 v116, v116
	v_exp_f32_e32 v117, v117
	v_exp_f32_e32 v118, v118
	v_add_f32_e32 v116, 1.0, v116
	v_add_f32_e32 v119, 1.0, v117
	v_add_f32_e32 v117, 1.0, v118
	v_rcp_f32_e32 v116, v116
	v_rcp_f32_e32 v117, v117
	v_mul_f32_e32 v118, 0xbfb8aa3b, v105
	v_exp_f32_e32 v120, v118
	v_rcp_f32_e32 v118, v119
	v_pk_mul_f32 v[108:109], v[108:109], v[116:117]
	v_mul_f32_e32 v116, 0xbfb8aa3b, v111
	v_pk_mul_f32 v[100:101], v[108:109], v[100:101]
	v_add_f32_e32 v108, 1.0, v120
	v_rcp_f32_e32 v119, v108
	v_mul_f32_e32 v109, 0xbfb8aa3b, v106
	v_mul_f32_e32 v108, 0xbfb8aa3b, v110
	v_exp_f32_e32 v109, v109
	v_exp_f32_e32 v108, v108
	v_exp_f32_e32 v117, v116
	v_mul_f32_e32 v116, 0xbfb8aa3b, v107
	v_pk_mul_f32 v[104:105], v[104:105], v[118:119]
	v_exp_f32_e32 v118, v116
	v_add_f32_e32 v109, 1.0, v109
	v_add_f32_e32 v108, 1.0, v108
	v_rcp_f32_e32 v116, v109
	v_add_f32_e32 v109, 1.0, v117
	v_rcp_f32_e32 v108, v108
	v_rcp_f32_e32 v109, v109
	v_add_f32_e32 v117, 1.0, v118
	v_rcp_f32_e32 v117, v117
	v_pk_mul_f32 v[104:105], v[104:105], v[96:97]
	v_pk_mul_f32 v[96:97], v[110:111], v[108:109]
	v_or_b32_e32 v108, 16, v153
	v_pk_mul_f32 v[102:103], v[96:97], v[102:103]
	v_pk_mul_f32 v[96:97], v[106:107], v[116:117]
	s_nop 0
	v_pk_mul_f32 v[106:107], v[96:97], v[98:99]
	v_cvt_pk_bf16_f32 v96, v100, v101
	v_mad_i64_i32 v[100:101], s[26:27], v108, s44, v[112:113]
	v_cvt_pk_bf16_f32 v97, v102, v103
	v_cvt_pk_bf16_f32 v98, v104, v105
	v_cvt_pk_bf16_f32 v99, v106, v107
	v_lshl_add_u64 v[100:101], v[100:101], 0, v[114:115]
	global_store_dwordx4 v[100:101], v[96:99], off
	s_nop 1
	v_mul_f32_e32 v96, 0xbfb8aa3b, v92
	v_mul_f32_e32 v97, 0xbfb8aa3b, v88
	v_mul_f32_e32 v98, 0xbfb8aa3b, v93
	v_exp_f32_e32 v96, v96
	v_exp_f32_e32 v97, v97
	v_exp_f32_e32 v98, v98
	v_add_f32_e32 v96, 1.0, v96
	v_add_f32_e32 v99, 1.0, v97
	v_add_f32_e32 v97, 1.0, v98
	v_rcp_f32_e32 v96, v96
	v_rcp_f32_e32 v97, v97
	v_mul_f32_e32 v98, 0xbfb8aa3b, v89
	v_exp_f32_e32 v100, v98
	v_rcp_f32_e32 v98, v99
	v_pk_mul_f32 v[92:93], v[92:93], v[96:97]
	v_mul_f32_e32 v96, 0xbfb8aa3b, v95
	v_pk_mul_f32 v[84:85], v[92:93], v[84:85]
	v_add_f32_e32 v92, 1.0, v100
	v_rcp_f32_e32 v99, v92
	v_mul_f32_e32 v93, 0xbfb8aa3b, v90
	v_mul_f32_e32 v92, 0xbfb8aa3b, v94
	v_exp_f32_e32 v93, v93
	v_exp_f32_e32 v92, v92
	v_exp_f32_e32 v97, v96
	v_mul_f32_e32 v96, 0xbfb8aa3b, v91
	v_pk_mul_f32 v[88:89], v[88:89], v[98:99]
	v_exp_f32_e32 v98, v96
	v_add_f32_e32 v93, 1.0, v93
	v_add_f32_e32 v92, 1.0, v92
	v_rcp_f32_e32 v96, v93
	v_add_f32_e32 v93, 1.0, v97
	v_rcp_f32_e32 v92, v92
	v_rcp_f32_e32 v93, v93
	v_add_f32_e32 v97, 1.0, v98
	v_rcp_f32_e32 v97, v97
	v_pk_mul_f32 v[88:89], v[88:89], v[80:81]
	v_pk_mul_f32 v[80:81], v[94:95], v[92:93]
	v_or_b32_e32 v92, 32, v153
	v_pk_mul_f32 v[86:87], v[80:81], v[86:87]
	v_pk_mul_f32 v[80:81], v[90:91], v[96:97]
	s_nop 0
	v_pk_mul_f32 v[90:91], v[80:81], v[82:83]
	v_cvt_pk_bf16_f32 v80, v84, v85
	v_mad_i64_i32 v[84:85], s[26:27], v92, s44, v[112:113]
	v_cvt_pk_bf16_f32 v81, v86, v87
	v_cvt_pk_bf16_f32 v82, v88, v89
	v_cvt_pk_bf16_f32 v83, v90, v91
	v_lshl_add_u64 v[84:85], v[84:85], 0, v[114:115]
	global_store_dwordx4 v[84:85], v[80:83], off
	s_nop 1
	v_mul_f32_e32 v80, 0xbfb8aa3b, v76
	v_mul_f32_e32 v81, 0xbfb8aa3b, v72
	v_mul_f32_e32 v82, 0xbfb8aa3b, v77
	v_exp_f32_e32 v80, v80
	v_exp_f32_e32 v81, v81
	v_exp_f32_e32 v82, v82
	v_add_f32_e32 v80, 1.0, v80
	v_add_f32_e32 v83, 1.0, v81
	v_add_f32_e32 v81, 1.0, v82
	v_rcp_f32_e32 v80, v80
	v_rcp_f32_e32 v81, v81
	v_mul_f32_e32 v82, 0xbfb8aa3b, v73
	v_exp_f32_e32 v84, v82
	v_rcp_f32_e32 v82, v83
	v_pk_mul_f32 v[76:77], v[76:77], v[80:81]
	v_mul_f32_e32 v80, 0xbfb8aa3b, v79
	v_pk_mul_f32 v[68:69], v[76:77], v[68:69]
	v_add_f32_e32 v76, 1.0, v84
	v_rcp_f32_e32 v83, v76
	v_mul_f32_e32 v77, 0xbfb8aa3b, v74
	v_mul_f32_e32 v76, 0xbfb8aa3b, v78
	v_exp_f32_e32 v77, v77
	v_exp_f32_e32 v76, v76
	v_exp_f32_e32 v81, v80
	v_mul_f32_e32 v80, 0xbfb8aa3b, v75
	v_pk_mul_f32 v[72:73], v[72:73], v[82:83]
	v_exp_f32_e32 v82, v80
	v_add_f32_e32 v77, 1.0, v77
	v_add_f32_e32 v76, 1.0, v76
	v_rcp_f32_e32 v80, v77
	v_add_f32_e32 v77, 1.0, v81
	v_rcp_f32_e32 v76, v76
	v_rcp_f32_e32 v77, v77
	v_add_f32_e32 v81, 1.0, v82
	v_rcp_f32_e32 v81, v81
	v_pk_mul_f32 v[72:73], v[72:73], v[64:65]
	v_pk_mul_f32 v[64:65], v[78:79], v[76:77]
	v_or_b32_e32 v76, 48, v153
	v_pk_mul_f32 v[70:71], v[64:65], v[70:71]
	v_pk_mul_f32 v[64:65], v[74:75], v[80:81]
	s_nop 0
	v_pk_mul_f32 v[74:75], v[64:65], v[66:67]
	v_cvt_pk_bf16_f32 v64, v68, v69
	v_mad_i64_i32 v[68:69], s[26:27], v76, s44, v[112:113]
	v_cvt_pk_bf16_f32 v65, v70, v71
	v_cvt_pk_bf16_f32 v66, v72, v73
	v_cvt_pk_bf16_f32 v67, v74, v75
	v_lshl_add_u64 v[68:69], v[68:69], 0, v[114:115]
	global_store_dwordx4 v[68:69], v[64:67], off
	v_add_u32_e32 v68, 0x80, v153
	s_nop 0
	v_mul_f32_e32 v64, 0xbfb8aa3b, v60
	v_mul_f32_e32 v65, 0xbfb8aa3b, v56
	v_mul_f32_e32 v66, 0xbfb8aa3b, v61
	v_exp_f32_e32 v64, v64
	v_exp_f32_e32 v65, v65
	v_exp_f32_e32 v66, v66
	v_add_f32_e32 v64, 1.0, v64
	v_add_f32_e32 v67, 1.0, v65
	v_add_f32_e32 v65, 1.0, v66
	v_rcp_f32_e32 v64, v64
	v_rcp_f32_e32 v65, v65
	v_mul_f32_e32 v66, 0xbfb8aa3b, v57
	v_exp_f32_e32 v69, v66
	v_rcp_f32_e32 v66, v67
	v_pk_mul_f32 v[60:61], v[60:61], v[64:65]
	v_mul_f32_e32 v64, 0xbfb8aa3b, v63
	v_pk_mul_f32 v[52:53], v[60:61], v[52:53]
	v_add_f32_e32 v60, 1.0, v69
	v_rcp_f32_e32 v67, v60
	v_mul_f32_e32 v61, 0xbfb8aa3b, v58
	v_mul_f32_e32 v60, 0xbfb8aa3b, v62
	v_exp_f32_e32 v61, v61
	v_exp_f32_e32 v60, v60
	v_exp_f32_e32 v65, v64
	v_mul_f32_e32 v64, 0xbfb8aa3b, v59
	v_pk_mul_f32 v[56:57], v[56:57], v[66:67]
	v_exp_f32_e32 v66, v64
	v_add_f32_e32 v61, 1.0, v61
	v_add_f32_e32 v60, 1.0, v60
	v_rcp_f32_e32 v64, v61
	v_add_f32_e32 v61, 1.0, v65
	v_rcp_f32_e32 v60, v60
	v_rcp_f32_e32 v61, v61
	v_add_f32_e32 v65, 1.0, v66
	v_rcp_f32_e32 v65, v65
	v_pk_mul_f32 v[56:57], v[56:57], v[48:49]
	v_pk_mul_f32 v[48:49], v[62:63], v[60:61]
	s_nop 0
	v_pk_mul_f32 v[54:55], v[48:49], v[54:55]
	v_pk_mul_f32 v[48:49], v[58:59], v[64:65]
	s_nop 0
	v_pk_mul_f32 v[58:59], v[48:49], v[50:51]
	v_cvt_pk_bf16_f32 v48, v52, v53
	v_mad_i64_i32 v[52:53], s[26:27], v68, s44, v[112:113]
	v_cvt_pk_bf16_f32 v49, v54, v55
	v_cvt_pk_bf16_f32 v50, v56, v57
	v_cvt_pk_bf16_f32 v51, v58, v59
	v_lshl_add_u64 v[52:53], v[52:53], 0, v[114:115]
	v_mov_b32_e32 v230, v52
	v_mov_b32_e32 v231, v53
	v_mov_b32_e32 v238, v48
	v_mov_b32_e32 v239, v49
	v_mov_b32_e32 v240, v50
	v_mov_b32_e32 v241, v51
	s_nop 1
	v_mul_f32_e32 v48, 0xbfb8aa3b, v44
	v_mul_f32_e32 v49, 0xbfb8aa3b, v40
	v_mul_f32_e32 v50, 0xbfb8aa3b, v45
	v_exp_f32_e32 v48, v48
	v_exp_f32_e32 v49, v49
	v_exp_f32_e32 v50, v50
	v_add_f32_e32 v48, 1.0, v48
	v_add_f32_e32 v51, 1.0, v49
	v_add_f32_e32 v49, 1.0, v50
	v_rcp_f32_e32 v48, v48
	v_rcp_f32_e32 v49, v49
	v_mul_f32_e32 v50, 0xbfb8aa3b, v41
	v_exp_f32_e32 v52, v50
	v_rcp_f32_e32 v50, v51
	v_pk_mul_f32 v[44:45], v[44:45], v[48:49]
	v_mul_f32_e32 v48, 0xbfb8aa3b, v47
	v_pk_mul_f32 v[36:37], v[44:45], v[36:37]
	v_add_f32_e32 v44, 1.0, v52
	v_rcp_f32_e32 v51, v44
	v_mul_f32_e32 v45, 0xbfb8aa3b, v42
	v_mul_f32_e32 v44, 0xbfb8aa3b, v46
	v_exp_f32_e32 v45, v45
	v_exp_f32_e32 v44, v44
	v_exp_f32_e32 v49, v48
	v_mul_f32_e32 v48, 0xbfb8aa3b, v43
	v_pk_mul_f32 v[40:41], v[40:41], v[50:51]
	v_exp_f32_e32 v50, v48
	v_add_f32_e32 v45, 1.0, v45
	v_add_f32_e32 v44, 1.0, v44
	v_rcp_f32_e32 v48, v45
	v_add_f32_e32 v45, 1.0, v49
	v_rcp_f32_e32 v44, v44
	v_rcp_f32_e32 v45, v45
	v_add_f32_e32 v49, 1.0, v50
	v_rcp_f32_e32 v49, v49
	v_pk_mul_f32 v[40:41], v[40:41], v[32:33]
	v_pk_mul_f32 v[32:33], v[46:47], v[44:45]
	v_add_u32_e32 v44, 0x90, v153
	v_pk_mul_f32 v[38:39], v[32:33], v[38:39]
	v_pk_mul_f32 v[32:33], v[42:43], v[48:49]
	s_nop 0
	v_pk_mul_f32 v[42:43], v[32:33], v[34:35]
	v_cvt_pk_bf16_f32 v32, v36, v37
	v_mad_i64_i32 v[36:37], s[26:27], v44, s44, v[112:113]
	v_cvt_pk_bf16_f32 v33, v38, v39
	v_cvt_pk_bf16_f32 v34, v40, v41
	v_cvt_pk_bf16_f32 v35, v42, v43
	v_lshl_add_u64 v[36:37], v[36:37], 0, v[114:115]
	v_mov_b32_e32 v232, v36
	v_mov_b32_e32 v233, v37
	v_mov_b32_e32 v242, v32
	v_mov_b32_e32 v243, v33
	v_mov_b32_e32 v244, v34
	v_mov_b32_e32 v245, v35
	s_nop 1
	v_mul_f32_e32 v32, 0xbfb8aa3b, v28
	v_mul_f32_e32 v33, 0xbfb8aa3b, v24
	v_mul_f32_e32 v34, 0xbfb8aa3b, v29
	v_exp_f32_e32 v32, v32
	v_exp_f32_e32 v33, v33
	v_exp_f32_e32 v34, v34
	v_add_f32_e32 v32, 1.0, v32
	v_add_f32_e32 v35, 1.0, v33
	v_add_f32_e32 v33, 1.0, v34
	v_rcp_f32_e32 v32, v32
	v_rcp_f32_e32 v33, v33
	v_mul_f32_e32 v34, 0xbfb8aa3b, v25
	v_exp_f32_e32 v36, v34
	v_rcp_f32_e32 v34, v35
	v_pk_mul_f32 v[28:29], v[28:29], v[32:33]
	v_mul_f32_e32 v32, 0xbfb8aa3b, v31
	v_pk_mul_f32 v[20:21], v[28:29], v[20:21]
	v_add_f32_e32 v28, 1.0, v36
	v_rcp_f32_e32 v35, v28
	v_mul_f32_e32 v29, 0xbfb8aa3b, v26
	v_mul_f32_e32 v28, 0xbfb8aa3b, v30
	v_exp_f32_e32 v29, v29
	v_exp_f32_e32 v28, v28
	v_exp_f32_e32 v33, v32
	v_mul_f32_e32 v32, 0xbfb8aa3b, v27
	v_pk_mul_f32 v[24:25], v[24:25], v[34:35]
	v_exp_f32_e32 v34, v32
	v_add_f32_e32 v29, 1.0, v29
	v_add_f32_e32 v28, 1.0, v28
	v_rcp_f32_e32 v32, v29
	v_add_f32_e32 v29, 1.0, v33
	v_rcp_f32_e32 v28, v28
	v_rcp_f32_e32 v29, v29
	v_add_f32_e32 v33, 1.0, v34
	v_rcp_f32_e32 v33, v33
	v_pk_mul_f32 v[24:25], v[24:25], v[16:17]
	v_pk_mul_f32 v[16:17], v[30:31], v[28:29]
	v_add_u32_e32 v28, 0xa0, v153
	v_pk_mul_f32 v[22:23], v[16:17], v[22:23]
	v_pk_mul_f32 v[16:17], v[26:27], v[32:33]
	s_nop 0
	v_pk_mul_f32 v[26:27], v[16:17], v[18:19]
	v_cvt_pk_bf16_f32 v16, v20, v21
	v_mad_i64_i32 v[20:21], s[26:27], v28, s44, v[112:113]
	v_cvt_pk_bf16_f32 v17, v22, v23
	v_cvt_pk_bf16_f32 v18, v24, v25
	v_cvt_pk_bf16_f32 v19, v26, v27
	v_lshl_add_u64 v[20:21], v[20:21], 0, v[114:115]
	v_mov_b32_e32 v234, v20
	v_mov_b32_e32 v235, v21
	v_mov_b32_e32 v246, v16
	v_mov_b32_e32 v247, v17
	v_mov_b32_e32 v248, v18
	v_mov_b32_e32 v249, v19
	s_nop 1
	v_mul_f32_e32 v16, 0xbfb8aa3b, v12
	v_mul_f32_e32 v17, 0xbfb8aa3b, v8
	v_mul_f32_e32 v18, 0xbfb8aa3b, v13
	v_exp_f32_e32 v16, v16
	v_exp_f32_e32 v17, v17
	v_exp_f32_e32 v18, v18
	v_add_f32_e32 v16, 1.0, v16
	v_add_f32_e32 v19, 1.0, v17
	v_add_f32_e32 v17, 1.0, v18
	v_rcp_f32_e32 v16, v16
	v_rcp_f32_e32 v17, v17
	v_mul_f32_e32 v18, 0xbfb8aa3b, v9
	v_exp_f32_e32 v20, v18
	v_rcp_f32_e32 v18, v19
	v_pk_mul_f32 v[12:13], v[12:13], v[16:17]
	v_mul_f32_e32 v16, 0xbfb8aa3b, v15
	v_pk_mul_f32 v[4:5], v[12:13], v[4:5]
	v_add_f32_e32 v12, 1.0, v20
	v_rcp_f32_e32 v19, v12
	v_mul_f32_e32 v13, 0xbfb8aa3b, v10
	v_mul_f32_e32 v12, 0xbfb8aa3b, v14
	v_exp_f32_e32 v13, v13
	v_exp_f32_e32 v12, v12
	v_exp_f32_e32 v17, v16
	v_mul_f32_e32 v16, 0xbfb8aa3b, v11
	v_pk_mul_f32 v[8:9], v[8:9], v[18:19]
	v_exp_f32_e32 v18, v16
	v_add_f32_e32 v13, 1.0, v13
	v_add_f32_e32 v12, 1.0, v12
	v_rcp_f32_e32 v16, v13
	v_add_f32_e32 v13, 1.0, v17
	v_rcp_f32_e32 v12, v12
	v_rcp_f32_e32 v13, v13
	v_add_f32_e32 v17, 1.0, v18
	v_rcp_f32_e32 v17, v17
	v_pk_mul_f32 v[8:9], v[8:9], v[0:1]
	v_pk_mul_f32 v[0:1], v[14:15], v[12:13]
	v_add_u32_e32 v12, 0xb0, v153
	v_pk_mul_f32 v[6:7], v[0:1], v[6:7]
	v_pk_mul_f32 v[0:1], v[10:11], v[16:17]
	s_nop 0
	v_pk_mul_f32 v[10:11], v[0:1], v[2:3]
	v_cvt_pk_bf16_f32 v0, v4, v5
	v_mad_i64_i32 v[4:5], s[26:27], v12, s44, v[112:113]
	v_cvt_pk_bf16_f32 v1, v6, v7
	v_cvt_pk_bf16_f32 v2, v8, v9
	v_cvt_pk_bf16_f32 v3, v10, v11
	v_lshl_add_u64 v[4:5], v[4:5], 0, v[114:115]
	v_mov_b32_e32 v236, v4
	v_mov_b32_e32 v237, v5
	v_mov_b32_e32 v250, v0
	v_mov_b32_e32 v251, v1
	v_mov_b32_e32 v252, v2
	v_mov_b32_e32 v253, v3
	s_mov_b32 s98, 1
	s_cbranch_vccnz .LBB0_853
	s_andn2_b64 vcc, exec, s[6:7]
	s_cbranch_vccnz .LBB0_852
	s_barrier
	s_branch .LBB0_852
.LBB0_863:
	s_cmp_eq_u32 s98, 0
	s_cbranch_scc1 .Lp7d_flushed
	global_store_dwordx4 v[230:231], v[238:241], off
	global_store_dwordx4 v[232:233], v[242:245], off
	global_store_dwordx4 v[234:235], v[246:249], off
	global_store_dwordx4 v[236:237], v[250:253], off
	s_mov_b32 s98, 0
